# group-A attention dense loop: waves 4-7 run one barrier interval behind waves 0-3 (mid-tile barrier before P.V, V DMA after it)
# speedup vs baseline: 1.0423x; 1.0094x over previous
.LBB0_235:
	s_or_b64 exec, exec, s[4:5]
	v_max_f32_e32 v35, 0xf149f2ca, v46
	v_cndmask_b32_e32 v224, v35, v196, vcc
	v_mul_f32_e32 v34, 0xbe38aa3b, v224
	v_fmamk_f32 v18, v18, 0x3e38aa3b, v34
	v_exp_f32_e32 v230, v18
	v_sub_f32_e32 v18, 0xf149f2ca, v35
	v_mul_f32_e32 v18, 0x3e38aa3b, v18
	v_exp_f32_e32 v18, v18
	v_fmamk_f32 v19, v19, 0x3e38aa3b, v34
	v_fmamk_f32 v20, v20, 0x3e38aa3b, v34
	v_fmamk_f32 v21, v21, 0x3e38aa3b, v34
	v_fmamk_f32 v22, v22, 0x3e38aa3b, v34
	v_fmamk_f32 v23, v23, 0x3e38aa3b, v34
	v_fmamk_f32 v24, v24, 0x3e38aa3b, v34
	v_fmamk_f32 v25, v25, 0x3e38aa3b, v34
	v_fmamk_f32 v26, v26, 0x3e38aa3b, v34
	v_fmamk_f32 v27, v27, 0x3e38aa3b, v34
	v_fmamk_f32 v28, v28, 0x3e38aa3b, v34
	v_fmamk_f32 v29, v29, 0x3e38aa3b, v34
	v_fmamk_f32 v30, v30, 0x3e38aa3b, v34
	v_fmamk_f32 v31, v31, 0x3e38aa3b, v34
	v_fmamk_f32 v32, v32, 0x3e38aa3b, v34
	v_fmamk_f32 v33, v33, 0x3e38aa3b, v34
	v_exp_f32_e32 v234, v19
	v_exp_f32_e32 v231, v20
	v_exp_f32_e32 v235, v21
	v_exp_f32_e32 v232, v22
	v_exp_f32_e32 v236, v23
	v_exp_f32_e32 v233, v24
	v_exp_f32_e32 v237, v25
	v_exp_f32_e32 v140, v26
	v_exp_f32_e32 v143, v27
	v_exp_f32_e32 v141, v28
	v_exp_f32_e32 v144, v29
	v_exp_f32_e32 v142, v30
	v_exp_f32_e32 v146, v31
	v_exp_f32_e32 v145, v32
	v_exp_f32_e32 v147, v33
	v_pk_fma_f32 v[124:125], v[16:17], s[92:93], v[34:35] op_sel_hi:[1,0,0]
	v_pk_fma_f32 v[138:139], v[2:3], s[92:93], v[34:35] op_sel_hi:[1,0,0]
	v_lshlrev_b32_e32 v2, 4, v205
	v_mov_b32_e32 v3, v1
	s_mov_b64 s[4:5], 0x104008
	v_mov_b32_e32 v16, v1
	v_mov_b32_e32 v17, v1
	v_cndmask_b32_e64 v222, v18, 1.0, vcc
	v_pk_fma_f32 v[126:127], v[14:15], s[92:93], v[34:35] op_sel_hi:[1,0,0]
	v_pk_fma_f32 v[128:129], v[12:13], s[92:93], v[34:35] op_sel_hi:[1,0,0]
	v_pk_fma_f32 v[130:131], v[10:11], s[92:93], v[34:35] op_sel_hi:[1,0,0]
	v_pk_fma_f32 v[132:133], v[8:9], s[92:93], v[34:35] op_sel_hi:[1,0,0]
	v_pk_fma_f32 v[134:135], v[6:7], s[92:93], v[34:35] op_sel_hi:[1,0,0]
	v_pk_fma_f32 v[136:137], v[4:5], s[92:93], v[34:35] op_sel_hi:[1,0,0]
	v_lshl_add_u64 v[182:183], v[168:169], 0, v[2:3]
	v_lshl_add_u64 v[184:185], v[42:43], 0, s[4:5]
	global_load_dword v254, v[184:185], off offset:-4
	v_mov_b32_e32 v2, v1
	v_mov_b32_e32 v4, v1
	v_mov_b32_e32 v5, v1
	v_mov_b32_e32 v6, v1
	v_mov_b32_e32 v7, v1
	v_mov_b32_e32 v8, v1
	v_mov_b32_e32 v9, v1
	v_mov_b32_e32 v10, v1
	v_mov_b32_e32 v11, v1
	v_mov_b32_e32 v12, v1
	v_mov_b32_e32 v13, v1
	v_mov_b32_e32 v14, v1
	v_mov_b32_e32 v15, v1
	v_mov_b64_e32 v[32:33], v[16:17]
	v_mov_b64_e32 v[48:49], v[16:17]
	v_mov_b64_e32 v[64:65], v[16:17]
	s_mov_b32 s33, 1
	v_lshl_add_u64 v[178:179], v[154:155], 0, v[0:1]
	v_lshl_add_u64 v[180:181], v[172:173], 0, v[0:1]
	s_mov_b32 s38, 2
	v_lshlrev_b32_e32 v0, 2, v205
	v_cmp_gt_u32_e64 s[10:11], 32, v207
	v_lshl_add_u32 v220, v203, 2, s36
	v_add_u32_e32 v223, 0x80, v206
	s_mov_b32 s39, 0
	v_mov_b32_e32 v218, 0
	v_mov_b64_e32 v[30:31], v[14:15]
	v_mov_b64_e32 v[28:29], v[12:13]
	v_mov_b64_e32 v[26:27], v[10:11]
	v_mov_b64_e32 v[24:25], v[8:9]
	v_mov_b64_e32 v[22:23], v[6:7]
	v_mov_b64_e32 v[20:21], v[4:5]
	v_mov_b64_e32 v[18:19], v[2:3]
	v_mov_b64_e32 v[46:47], v[14:15]
	v_mov_b64_e32 v[44:45], v[12:13]
	v_mov_b64_e32 v[42:43], v[10:11]
	v_mov_b64_e32 v[40:41], v[8:9]
	v_mov_b64_e32 v[38:39], v[6:7]
	v_mov_b64_e32 v[36:37], v[4:5]
	v_mov_b64_e32 v[34:35], v[2:3]
	v_mov_b64_e32 v[62:63], v[14:15]
	v_mov_b64_e32 v[60:61], v[12:13]
	v_mov_b64_e32 v[58:59], v[10:11]
	v_mov_b64_e32 v[56:57], v[8:9]
	v_mov_b64_e32 v[54:55], v[6:7]
	v_mov_b64_e32 v[52:53], v[4:5]
	v_mov_b64_e32 v[50:51], v[2:3]
	v_readfirstlane_b32 s44, v204
	v_and_b32_e32 v66, 7, v206
	v_lshlrev_b32_e32 v66, 4, v66
	v_xor_b32_e32 v66, v66, v208
	v_add_u32_e32 v67, 0x80, v206
	v_mul_lo_u32 v67, v67, s67
	s_lshl_b32 s44, s44, 4
	v_add_u32_e32 v66, v66, v67
	v_mov_b32_e32 v67, 0
	s_mov_b64 s[62:63], 0x4c000
	v_lshl_add_u64 v[116:117], v[172:173], 0, v[66:67]
	v_lshl_add_u64 v[118:119], v[116:117], 0, s[62:63]
	v_bfe_u32 v68, v204, 2, 2
	v_bfe_u32 v69, v204, 7, 1
	v_lshl_or_b32 v68, v69, 2, v68
	v_bfe_u32 v69, v204, 4, 1
	v_lshl_or_b32 v68, v69, 3, v68
	v_bfe_u32 v69, v204, 8, 1
	v_lshl_or_b32 v68, v69, 4, v68
	v_add_u32_e32 v68, 0x80, v68
	v_mul_lo_u32 v68, v68, s67
	v_and_b32_e32 v69, 3, v204
	v_lshlrev_b32_e32 v69, 4, v69
	v_bfe_u32 v70, v204, 5, 2
	v_lshl_or_b32 v69, v70, 6, v69
	v_add_u32_e32 v68, v68, v69
	v_mov_b32_e32 v69, 0
	v_lshl_add_u64 v[120:121], v[154:155], 0, v[68:69]
	v_lshl_add_u64 v[122:123], v[120:121], 0, s[62:63]
	s_mov_b64 s[62:63], 0x98000
	s_add_i32 s45, s44, 0x14000
	s_mov_b32 m0, s45
	s_mov_b64 exec, s[8:9]
	s_add_i32 s45, s45, 0x2000
	global_load_lds_dwordx4 v[116:117], off
	s_mov_b32 m0, s45
	s_nop 0
	global_load_lds_dwordx4 v[118:119], off
	s_mov_b64 exec, -1
	v_lshl_add_u64 v[116:117], v[116:117], 0, s[62:63]
	v_lshl_add_u64 v[118:119], v[118:119], 0, s[62:63]
	s_waitcnt vmcnt(2)
	s_mov_b32 s4, 2
	s_waitcnt lgkmcnt(0)
	s_barrier
	s_cmpk_lt_u32 s44, 0x1000
	s_cbranch_scc1 .LskewA_in
	s_barrier
.LskewA_in:
.LBB0_236:
	s_mov_b32 s40, s4
	v_mov_b32_e32 v68, 0
	s_waitcnt lgkmcnt(0)
	v_sub_u32_e32 v66, v254, v201
	v_cmp_lt_i32_e32 vcc, s87, v66
	v_cmp_gt_i32_e64 s[12:13], s84, v66
	s_and_saveexec_b64 s[4:5], s[12:13]
	v_mov_b32_e32 v66, s86
	ds_read_b32 v68, v66
	s_or_b64 exec, exec, s[4:5]
	global_load_dword v253, v[184:185], off
	s_lshl_b32 s45, s39, 14
	s_add_i32 s45, s45, s44
	s_add_i32 s48, s45, 0xc000
	s_mov_b32 m0, s48
	s_mov_b64 exec, s[8:9]
	s_add_i32 s48, s48, 0x2000
	global_load_lds_dwordx4 v[116:117], off
	s_mov_b32 m0, s48
	s_nop 0
	global_load_lds_dwordx4 v[118:119], off
	s_mov_b64 exec, -1
	v_lshl_add_u64 v[116:117], v[116:117], 0, s[62:63]
	v_lshl_add_u64 v[118:119], v[118:119], 0, s[62:63]
	s_lshl_b32 s43, s33, 14
	v_add_u32_e32 v66, s43, v221
	v_add_u32_e32 v67, v66, v210
	ds_read_b128 v[226:229], v67 offset:49152
	ds_read_b128 v[238:241], v67 offset:57344
	s_waitcnt lgkmcnt(2)
	v_mov_b32_e32 v69, v68
	v_mov_b32_e32 v70, v68
	v_mov_b32_e32 v71, v68
	v_mov_b32_e32 v72, v68
	v_mov_b32_e32 v73, v68
	v_mov_b32_e32 v74, v68
	v_mov_b32_e32 v75, v68
	v_mov_b32_e32 v76, v68
	v_mov_b32_e32 v77, v68
	v_mov_b32_e32 v78, v68
	v_mov_b32_e32 v79, v68
	v_mov_b32_e32 v80, v68
	v_mov_b32_e32 v81, v68
	v_mov_b32_e32 v82, v68
	v_mov_b32_e32 v83, v68
	v_add_u32_e32 v67, v66, v212
	v_exp_f32_e32 v219, v136
	s_waitcnt lgkmcnt(1)
	v_mfma_f32_32x32x16_bf16 v[84:99], v[226:229], v[100:103], v[68:83]
	v_exp_f32_e32 v130, v130
	v_exp_f32_e32 v131, v131
	v_exp_f32_e32 v128, v128
	v_exp_f32_e32 v129, v129
	v_exp_f32_e32 v126, v126
	v_exp_f32_e32 v127, v127
	v_exp_f32_e32 v124, v124
	s_waitcnt lgkmcnt(0)
	v_mfma_f32_32x32x16_bf16 v[68:83], v[238:241], v[100:103], v[68:83]
	ds_read_b128 v[226:229], v67 offset:49152
	ds_read_b128 v[238:241], v67 offset:57344
	v_add_u32_e32 v67, v66, v213
	v_add_u32_e32 v66, v66, v214
	v_exp_f32_e32 v125, v125
	s_waitcnt lgkmcnt(0)
	v_mfma_f32_32x32x16_bf16 v[68:83], v[238:241], v[104:107], v[68:83]
	v_mfma_f32_32x32x16_bf16 v[84:99], v[226:229], v[104:107], v[84:99]
	ds_read_b128 v[226:229], v67 offset:49152
	ds_read_b128 v[238:241], v67 offset:57344
	v_exp_f32_e32 v67, v139
	s_waitcnt lgkmcnt(0)
	v_mfma_f32_32x32x16_bf16 v[68:83], v[238:241], v[108:111], v[68:83]
	v_mfma_f32_32x32x16_bf16 v[84:99], v[226:229], v[108:111], v[84:99]
	ds_read_b128 v[226:229], v66 offset:49152
	ds_read_b128 v[238:241], v66 offset:57344
	v_exp_f32_e32 v66, v138
	s_waitcnt lgkmcnt(0)
	v_mfma_f32_32x32x16_bf16 v[68:83], v[238:241], v[112:115], v[68:83]
	v_exp_f32_e32 v238, v132
	v_add_f32_e32 v132, 0, v230
	v_add_f32_e32 v132, v234, v132
	v_add_f32_e32 v132, v231, v132
	v_add_f32_e32 v132, v235, v132
	v_add_f32_e32 v132, v232, v132
	v_add_f32_e32 v132, v236, v132
	v_add_f32_e32 v132, v233, v132
	v_add_f32_e32 v132, v237, v132
	v_add_f32_e32 v132, v140, v132
	v_add_f32_e32 v132, v143, v132
	v_add_f32_e32 v132, v141, v132
	v_add_f32_e32 v132, v144, v132
	v_add_f32_e32 v132, v142, v132
	v_add_f32_e32 v132, v146, v132
	v_add_f32_e32 v132, v145, v132
	v_mfma_f32_32x32x16_bf16 v[84:99], v[226:229], v[112:115], v[84:99]
	v_exp_f32_e32 v227, v137
	v_add_f32_e32 v132, v147, v132
	v_exp_f32_e32 v228, v134
	v_add_f32_e32 v132, v66, v132
	v_exp_f32_e32 v229, v135
	v_add_f32_e32 v132, v67, v132
	v_add_f32_e32 v132, v219, v132
	v_exp_f32_e32 v239, v133
	v_add_f32_e32 v132, v227, v132
	v_add_f32_e32 v132, v228, v132
	v_add_f32_e32 v132, v229, v132
	v_add_f32_e32 v132, v238, v132
	v_add_f32_e32 v132, v239, v132
	v_add_f32_e32 v132, v130, v132
	v_add_f32_e32 v132, v131, v132
	v_add_f32_e32 v132, v128, v132
	v_add_f32_e32 v132, v129, v132
	v_add_f32_e32 v132, v126, v132
	v_add_f32_e32 v132, v127, v132
	v_add_f32_e32 v132, v124, v132
	v_add_f32_e32 v225, v125, v132
	ds_bpermute_b32 v226, v187, v225
	v_cvt_pk_bf16_f32 v132, v230, v234
	v_cvt_pk_bf16_f32 v133, v231, v235
	v_cvt_pk_bf16_f32 v134, v232, v236
	v_cvt_pk_bf16_f32 v135, v233, v237
	v_cvt_pk_bf16_f32 v136, v140, v143
	v_cvt_pk_bf16_f32 v137, v141, v144
	v_cvt_pk_bf16_f32 v138, v142, v146
	v_cvt_pk_bf16_f32 v139, v145, v147
	v_cvt_pk_bf16_f32 v140, v66, v67
	v_cvt_pk_bf16_f32 v141, v219, v227
	v_cvt_pk_bf16_f32 v142, v228, v229
	v_cvt_pk_bf16_f32 v143, v238, v239
	v_cvt_pk_bf16_f32 v144, v130, v131
	v_cvt_pk_bf16_f32 v145, v128, v129
	v_cvt_pk_bf16_f32 v146, v126, v127
	v_cvt_pk_bf16_f32 v147, v124, v125
	s_nop 0
	v_permlane32_swap_b32_e32 v132, v134
	v_permlane32_swap_b32_e32 v133, v135
	v_permlane32_swap_b32_e32 v136, v138
	v_permlane32_swap_b32_e32 v137, v139
	v_permlane32_swap_b32_e32 v140, v142
	v_permlane32_swap_b32_e32 v141, v143
	v_permlane32_swap_b32_e32 v144, v146
	v_permlane32_swap_b32_e32 v145, v147
	s_waitcnt vmcnt(2)
	s_barrier
	s_lshl_b32 s45, s40, 14
	s_add_i32 s45, s45, s44
	s_mov_b32 m0, s45
	s_add_i32 s45, s45, 0x2000
	global_load_lds_dwordx4 v[120:121], off
	s_mov_b32 m0, s45
	v_lshl_add_u64 v[120:121], v[120:121], 0, s[62:63]
	global_load_lds_dwordx4 v[122:123], off
	v_lshl_add_u64 v[122:123], v[122:123], 0, s[62:63]
	s_lshl_b32 s42, s39, 14
	v_add_u32_e32 v219, s42, v188
	ds_read_b64_tr_b16 v[228:229], v219 offset:0
	ds_read_b64_tr_b16 v[230:231], v219 offset:0x800
	ds_read_b64_tr_b16 v[232:233], v219 offset:0x1000
	ds_read_b64_tr_b16 v[234:235], v219 offset:0x1800
	ds_read_b64_tr_b16 v[236:237], v219 offset:0x2000
	ds_read_b64_tr_b16 v[238:239], v219 offset:0x2800
	ds_read_b64_tr_b16 v[240:241], v219 offset:0x3000
	ds_read_b64_tr_b16 v[242:243], v219 offset:0x3800
	s_waitcnt lgkmcnt(0)
	s_nop 0
	v_mfma_f32_32x32x16_bf16 v[50:65], v[132:135], v[228:231], v[50:65]
	ds_read_b64_tr_b16 v[228:229], v219 offset:0x200
	ds_read_b64_tr_b16 v[230:231], v219 offset:0xa00
	v_mfma_f32_32x32x16_bf16 v[50:65], v[136:139], v[232:235], v[50:65]
	ds_read_b64_tr_b16 v[232:233], v219 offset:0x1200
	ds_read_b64_tr_b16 v[234:235], v219 offset:0x1a00
	v_mfma_f32_32x32x16_bf16 v[50:65], v[140:143], v[236:239], v[50:65]
	ds_read_b64_tr_b16 v[236:237], v219 offset:0x2200
	ds_read_b64_tr_b16 v[238:239], v219 offset:0x2a00
	v_mfma_f32_32x32x16_bf16 v[50:65], v[144:147], v[240:243], v[50:65]
	ds_read_b64_tr_b16 v[240:241], v219 offset:0x3200
	ds_read_b64_tr_b16 v[242:243], v219 offset:0x3a00
	s_waitcnt lgkmcnt(0)
	v_mfma_f32_32x32x16_bf16 v[34:49], v[132:135], v[228:231], v[34:49]
	ds_read_b64_tr_b16 v[228:229], v219 offset:0x400
	ds_read_b64_tr_b16 v[230:231], v219 offset:0xc00
	v_mfma_f32_32x32x16_bf16 v[34:49], v[136:139], v[232:235], v[34:49]
	ds_read_b64_tr_b16 v[232:233], v219 offset:0x1400
	ds_read_b64_tr_b16 v[234:235], v219 offset:0x1c00
	v_mfma_f32_32x32x16_bf16 v[34:49], v[140:143], v[236:239], v[34:49]
	ds_read_b64_tr_b16 v[236:237], v219 offset:0x2400
	ds_read_b64_tr_b16 v[238:239], v219 offset:0x2c00
	v_mfma_f32_32x32x16_bf16 v[34:49], v[144:147], v[240:243], v[34:49]
	ds_read_b64_tr_b16 v[240:241], v219 offset:0x3400
	ds_read_b64_tr_b16 v[242:243], v219 offset:0x3c00
	s_waitcnt lgkmcnt(0)
	v_mfma_f32_32x32x16_bf16 v[18:33], v[132:135], v[228:231], v[18:33]
	ds_read_b64_tr_b16 v[228:229], v219 offset:0x600
	ds_read_b64_tr_b16 v[230:231], v219 offset:0xe00
	v_mfma_f32_32x32x16_bf16 v[18:33], v[136:139], v[232:235], v[18:33]
	ds_read_b64_tr_b16 v[232:233], v219 offset:0x1600
	ds_read_b64_tr_b16 v[234:235], v219 offset:0x1e00
	v_mfma_f32_32x32x16_bf16 v[18:33], v[140:143], v[236:239], v[18:33]
	ds_read_b64_tr_b16 v[236:237], v219 offset:0x2600
	ds_read_b64_tr_b16 v[238:239], v219 offset:0x2e00
	v_mfma_f32_32x32x16_bf16 v[18:33], v[144:147], v[240:243], v[18:33]
	ds_read_b64_tr_b16 v[240:241], v219 offset:0x3600
	ds_read_b64_tr_b16 v[242:243], v219 offset:0x3e00
	s_waitcnt lgkmcnt(0)
	v_mfma_f32_32x32x16_bf16 v[2:17], v[132:135], v[228:231], v[2:17]
	v_mfma_f32_32x32x16_bf16 v[2:17], v[136:139], v[232:235], v[2:17]
	v_mfma_f32_32x32x16_bf16 v[2:17], v[140:143], v[236:239], v[2:17]
	v_mfma_f32_32x32x16_bf16 v[2:17], v[144:147], v[240:243], v[2:17]
	s_and_saveexec_b64 s[4:5], vcc
	s_cbranch_execz .LBB0_242
	flat_load_dwordx4 v[132:135], v[182:183] offset:256
	flat_load_dwordx4 v[136:139], v[182:183] offset:384
	flat_load_dwordx4 v[140:143], v[182:183] offset:288
	flat_load_dwordx4 v[144:147], v[182:183] offset:416
	flat_load_dwordx4 v[228:231], v[182:183] offset:320
	flat_load_dwordx4 v[232:235], v[182:183] offset:448
	flat_load_dwordx4 v[236:239], v[182:183] offset:352
	flat_load_dwordx4 v[240:243], v[182:183] offset:480
	s_waitcnt vmcnt(0) lgkmcnt(0)
	v_sub_u32_e32 v66, v132, v167
	v_sub_u32_e32 v67, v136, v167
	v_sub_u32_e32 v132, v133, v167
	v_sub_u32_e32 v133, v137, v167
	v_sub_u32_e32 v134, v134, v167
	v_sub_u32_e32 v136, v138, v167
	v_sub_u32_e32 v135, v135, v167
	v_sub_u32_e32 v137, v139, v167
	v_sub_u32_e32 v138, v140, v167
	v_sub_u32_e32 v139, v144, v167
	v_sub_u32_e32 v140, v141, v167
	v_sub_u32_e32 v141, v145, v167
	v_sub_u32_e32 v142, v142, v167
	v_sub_u32_e32 v144, v146, v167
	v_sub_u32_e32 v143, v143, v167
	v_sub_u32_e32 v145, v147, v167
	v_sub_u32_e32 v146, v228, v167
	v_sub_u32_e32 v228, v233, v167
	v_med3_i32 v66, v66, s87, v197
	v_med3_i32 v67, v67, s87, v197
	v_med3_i32 v132, v132, s87, v197
	v_med3_i32 v133, v133, s87, v197
	v_med3_i32 v134, v134, s87, v197
	v_med3_i32 v136, v136, s87, v197
	v_med3_i32 v135, v135, s87, v197
	v_med3_i32 v137, v137, s87, v197
	v_med3_i32 v138, v138, s87, v197
	v_med3_i32 v139, v139, s87, v197
	v_med3_i32 v141, v141, s87, v197
	v_med3_i32 v142, v142, s87, v197
	v_med3_i32 v144, v144, s87, v197
	v_med3_i32 v143, v143, s87, v197
	v_med3_i32 v145, v145, s87, v197
	v_sub_u32_e32 v227, v229, v167
	v_med3_i32 v140, v140, s87, v197
	v_med3_i32 v228, v228, s87, v197
	v_lshl_add_u32 v66, v66, 2, s86
	v_lshl_add_u32 v67, v67, 2, s86
	v_lshl_add_u32 v229, v132, 2, s86
	v_lshl_add_u32 v133, v133, 2, s86
	v_lshl_add_u32 v134, v134, 2, s86
	v_lshl_add_u32 v136, v136, 2, s86
	v_lshl_add_u32 v135, v135, 2, s86
	v_lshl_add_u32 v137, v137, 2, s86
	v_lshl_add_u32 v138, v138, 2, s86
	v_lshl_add_u32 v139, v139, 2, s86
	v_lshl_add_u32 v141, v141, 2, s86
	v_lshl_add_u32 v142, v142, 2, s86
	v_lshl_add_u32 v144, v144, 2, s86
	v_lshl_add_u32 v143, v143, 2, s86
	v_lshl_add_u32 v145, v145, 2, s86
	v_sub_u32_e32 v147, v232, v167
	v_lshl_add_u32 v232, v140, 2, s86
	v_lshl_add_u32 v233, v228, 2, s86
	ds_read_b32 v66, v66 offset:1220
	ds_read_b32 v132, v67 offset:1220
	ds_read_b32 v67, v229 offset:1220
	ds_read_b32 v133, v133 offset:1220
	ds_read_b32 v134, v134 offset:1220
	ds_read_b32 v136, v136 offset:1220
	ds_read_b32 v135, v135 offset:1220
	ds_read_b32 v137, v137 offset:1220
	ds_read_b32 v138, v138 offset:1220
	ds_read_b32 v140, v139 offset:1220
	ds_read_b32 v139, v232 offset:1220
	ds_read_b32 v141, v141 offset:1220
	ds_read_b32 v142, v142 offset:1220
	ds_read_b32 v144, v144 offset:1220
	ds_read_b32 v143, v143 offset:1220
	ds_read_b32 v145, v145 offset:1220
	v_sub_u32_e32 v228, v230, v167
	v_sub_u32_e32 v229, v234, v167
	v_med3_i32 v228, v228, s87, v197
	v_med3_i32 v229, v229, s87, v197
	v_lshl_add_u32 v230, v228, 2, s86
	v_lshl_add_u32 v232, v229, 2, s86
	v_sub_u32_e32 v228, v231, v167
	v_sub_u32_e32 v229, v235, v167
	v_med3_i32 v146, v146, s87, v197
	v_med3_i32 v147, v147, s87, v197
	v_med3_i32 v228, v228, s87, v197
	v_med3_i32 v229, v229, s87, v197
	v_med3_i32 v227, v227, s87, v197
	v_lshl_add_u32 v146, v146, 2, s86
	v_lshl_add_u32 v147, v147, 2, s86
	v_lshl_add_u32 v231, v228, 2, s86
	v_lshl_add_u32 v234, v229, 2, s86
	v_lshl_add_u32 v227, v227, 2, s86
	ds_read_b32 v146, v146 offset:1220
	ds_read_b32 v228, v147 offset:1220
	ds_read_b32 v147, v227 offset:1220
	ds_read_b32 v229, v233 offset:1220
	ds_read_b32 v230, v230 offset:1220
	ds_read_b32 v232, v232 offset:1220
	ds_read_b32 v231, v231 offset:1220
	ds_read_b32 v233, v234 offset:1220
	v_sub_u32_e32 v234, v240, v167
	v_med3_i32 v234, v234, s87, v197
	v_sub_u32_e32 v227, v236, v167
	v_lshl_add_u32 v235, v234, 2, s86
	v_sub_u32_e32 v234, v237, v167
	v_sub_u32_e32 v236, v241, v167
	v_med3_i32 v234, v234, s87, v197
	v_med3_i32 v236, v236, s87, v197
	v_lshl_add_u32 v237, v234, 2, s86
	v_lshl_add_u32 v244, v236, 2, s86
	v_sub_u32_e32 v234, v238, v167
	v_sub_u32_e32 v236, v242, v167
	v_med3_i32 v234, v234, s87, v197
	v_med3_i32 v236, v236, s87, v197
	v_lshl_add_u32 v238, v234, 2, s86
	v_lshl_add_u32 v240, v236, 2, s86
	v_sub_u32_e32 v234, v239, v167
	v_sub_u32_e32 v236, v243, v167
	v_med3_i32 v227, v227, s87, v197
	v_med3_i32 v234, v234, s87, v197
	v_med3_i32 v236, v236, s87, v197
	v_lshl_add_u32 v227, v227, 2, s86
	v_lshl_add_u32 v239, v234, 2, s86
	v_lshl_add_u32 v241, v236, 2, s86
	ds_read_b32 v234, v227 offset:1220
	ds_read_b32 v236, v235 offset:1220
	ds_read_b32 v238, v238 offset:1220
	ds_read_b32 v239, v239 offset:1220
	ds_read_b32 v235, v237 offset:1220
	ds_read_b32 v241, v241 offset:1220
	ds_read_b32 v240, v240 offset:1220
	ds_read_b32 v237, v244 offset:1220
	s_waitcnt lgkmcnt(4)
	v_pk_add_f32 v[98:99], v[98:99], v[238:239]
	s_waitcnt lgkmcnt(3)
	v_pk_add_f32 v[96:97], v[96:97], v[234:235]
	v_pk_add_f32 v[94:95], v[94:95], v[230:231]
	v_pk_add_f32 v[92:93], v[92:93], v[146:147]
	v_pk_add_f32 v[90:91], v[90:91], v[142:143]
	v_pk_add_f32 v[88:89], v[88:89], v[138:139]
	v_pk_add_f32 v[86:87], v[86:87], v[134:135]
	v_pk_add_f32 v[84:85], v[84:85], v[66:67]
	s_waitcnt lgkmcnt(1)
	v_pk_add_f32 v[82:83], v[82:83], v[240:241]
	s_waitcnt lgkmcnt(0)
	v_pk_add_f32 v[80:81], v[80:81], v[236:237]
	v_pk_add_f32 v[78:79], v[78:79], v[232:233]
	v_pk_add_f32 v[76:77], v[76:77], v[228:229]
	v_pk_add_f32 v[74:75], v[74:75], v[144:145]
	v_pk_add_f32 v[72:73], v[72:73], v[140:141]
	v_pk_add_f32 v[70:71], v[70:71], v[136:137]
	v_pk_add_f32 v[68:69], v[68:69], v[132:133]

.LBB0_248:
	s_waitcnt lgkmcnt(0)
	s_barrier
	s_waitcnt lgkmcnt(0)
	v_sub_u32_e32 v66, v253, v201
	v_cmp_lt_i32_e32 vcc, s87, v66
	v_cmp_gt_i32_e64 s[14:15], s84, v66
	v_mov_b32_e32 v66, 0
	s_and_saveexec_b64 s[4:5], s[14:15]
	v_mov_b32_e32 v66, s86
	ds_read_b32 v66, v66
	s_or_b64 exec, exec, s[4:5]
	global_load_dword v254, v[184:185], off offset:4
	s_lshl_b32 s45, s33, 14
	s_add_i32 s45, s45, s44
	s_add_i32 s48, s45, 0xc000
	s_mov_b32 m0, s48
	s_mov_b64 exec, s[8:9]
	s_add_i32 s48, s48, 0x2000
	global_load_lds_dwordx4 v[116:117], off
	s_mov_b32 m0, s48
	s_nop 0
	global_load_lds_dwordx4 v[118:119], off
	s_mov_b64 exec, -1
	v_lshl_add_u64 v[116:117], v[116:117], 0, s[62:63]
	v_lshl_add_u64 v[118:119], v[118:119], 0, s[62:63]
	v_cndmask_b32_e64 v224, v67, v224, s[12:13]
	v_mul_f32_e32 v132, 0xbe38aa3b, v224
	v_fmamk_f32 v138, v99, 0x3e38aa3b, v132
	v_exp_f32_e32 v139, v138
	v_add_u32_e32 v138, s41, v221
	v_fmamk_f32 v242, v82, 0x3e38aa3b, v132
	v_add_u32_e32 v82, v138, v210
	ds_read_b128 v[140:143], v82 offset:49152
	ds_read_b128 v[144:147], v82 offset:57344
	v_fmamk_f32 v67, v84, 0x3e38aa3b, v132
	v_fmamk_f32 v84, v85, 0x3e38aa3b, v132
	v_fmamk_f32 v85, v86, 0x3e38aa3b, v132
	v_fmamk_f32 v86, v87, 0x3e38aa3b, v132
	v_fmamk_f32 v87, v88, 0x3e38aa3b, v132
	v_fmamk_f32 v88, v89, 0x3e38aa3b, v132
	v_fmamk_f32 v89, v90, 0x3e38aa3b, v132
	v_fmamk_f32 v90, v91, 0x3e38aa3b, v132
	v_fmamk_f32 v91, v92, 0x3e38aa3b, v132
	v_fmamk_f32 v92, v93, 0x3e38aa3b, v132
	v_fmamk_f32 v93, v94, 0x3e38aa3b, v132
	v_fmamk_f32 v94, v95, 0x3e38aa3b, v132
	v_fmamk_f32 v95, v96, 0x3e38aa3b, v132
	v_fmamk_f32 v96, v97, 0x3e38aa3b, v132
	v_fmamk_f32 v97, v98, 0x3e38aa3b, v132
	v_fmamk_f32 v228, v68, 0x3e38aa3b, v132
	v_fmamk_f32 v229, v69, 0x3e38aa3b, v132
	v_fmamk_f32 v230, v70, 0x3e38aa3b, v132
	v_fmamk_f32 v231, v71, 0x3e38aa3b, v132
	v_fmamk_f32 v232, v72, 0x3e38aa3b, v132
	v_fmamk_f32 v233, v73, 0x3e38aa3b, v132
	v_fmamk_f32 v234, v74, 0x3e38aa3b, v132
	v_fmamk_f32 v235, v75, 0x3e38aa3b, v132
	v_fmamk_f32 v236, v76, 0x3e38aa3b, v132
	v_fmamk_f32 v237, v77, 0x3e38aa3b, v132
	v_fmamk_f32 v238, v78, 0x3e38aa3b, v132
	v_fmamk_f32 v239, v79, 0x3e38aa3b, v132
	v_fmamk_f32 v240, v80, 0x3e38aa3b, v132
	v_fmamk_f32 v241, v81, 0x3e38aa3b, v132
	v_exp_f32_e32 v125, v67
	s_waitcnt lgkmcnt(2)
	v_mov_b32_e32 v67, v66
	v_mov_b32_e32 v68, v66
	v_mov_b32_e32 v69, v66
	v_mov_b32_e32 v70, v66
	v_mov_b32_e32 v71, v66
	v_mov_b32_e32 v72, v66
	v_mov_b32_e32 v73, v66
	v_mov_b32_e32 v74, v66
	v_mov_b32_e32 v75, v66
	v_mov_b32_e32 v76, v66
	v_mov_b32_e32 v77, v66
	v_mov_b32_e32 v78, v66
	v_mov_b32_e32 v79, v66
	v_mov_b32_e32 v80, v66
	v_mov_b32_e32 v81, v66
	v_fmac_f32_e32 v132, 0x3e38aa3b, v83
	v_exp_f32_e32 v128, v84
	v_exp_f32_e32 v129, v85
	v_exp_f32_e32 v133, v86
	v_exp_f32_e32 v134, v87
	v_exp_f32_e32 v135, v88
	v_exp_f32_e32 v136, v89
	v_exp_f32_e32 v137, v90
	v_exp_f32_e32 v98, v91
	v_exp_f32_e32 v99, v92
	v_exp_f32_e32 v124, v93
	v_exp_f32_e32 v126, v94
	v_exp_f32_e32 v127, v95
	v_exp_f32_e32 v130, v96
	v_exp_f32_e32 v131, v97
	s_waitcnt lgkmcnt(1)
	v_mfma_f32_32x32x16_bf16 v[82:97], v[140:143], v[100:103], v[66:81]
	s_waitcnt lgkmcnt(0)
	v_mfma_f32_32x32x16_bf16 v[66:81], v[144:147], v[100:103], v[66:81]
	v_add_u32_e32 v144, v138, v212
	ds_read_b128 v[140:143], v144 offset:49152
	ds_read_b128 v[144:147], v144 offset:57344
	s_waitcnt lgkmcnt(1)
	v_mfma_f32_32x32x16_bf16 v[82:97], v[140:143], v[104:107], v[82:97]
	s_waitcnt lgkmcnt(0)
	v_mfma_f32_32x32x16_bf16 v[66:81], v[144:147], v[104:107], v[66:81]
	v_add_u32_e32 v144, v138, v213
	ds_read_b128 v[140:143], v144 offset:49152
	ds_read_b128 v[144:147], v144 offset:57344
	v_add_u32_e32 v138, v138, v214
	s_waitcnt lgkmcnt(1)
	v_mfma_f32_32x32x16_bf16 v[82:97], v[140:143], v[108:111], v[82:97]
	s_waitcnt lgkmcnt(0)
	v_mfma_f32_32x32x16_bf16 v[66:81], v[144:147], v[108:111], v[66:81]
	ds_read_b128 v[140:143], v138 offset:49152
	ds_read_b128 v[144:147], v138 offset:57344
	s_waitcnt lgkmcnt(1)
	v_mfma_f32_32x32x16_bf16 v[82:97], v[140:143], v[112:115], v[82:97]
	v_exp_f32_e32 v143, v231
	v_exp_f32_e32 v231, v237
	v_exp_f32_e32 v237, v132
	v_add_f32_e32 v132, 0, v125
	v_add_f32_e32 v132, v128, v132
	v_add_f32_e32 v132, v129, v132
	v_add_f32_e32 v132, v133, v132
	v_add_f32_e32 v132, v134, v132
	v_add_f32_e32 v132, v135, v132
	v_add_f32_e32 v132, v136, v132
	v_add_f32_e32 v132, v137, v132
	v_add_f32_e32 v132, v98, v132
	v_add_f32_e32 v132, v99, v132
	v_add_f32_e32 v132, v124, v132
	v_add_f32_e32 v132, v126, v132
	v_exp_f32_e32 v140, v228
	v_add_f32_e32 v132, v127, v132
	v_exp_f32_e32 v141, v229
	v_add_f32_e32 v132, v130, v132
	v_exp_f32_e32 v142, v230
	v_add_f32_e32 v132, v131, v132
	v_add_f32_e32 v132, v139, v132
	s_waitcnt lgkmcnt(0)
	v_mfma_f32_32x32x16_bf16 v[66:81], v[144:147], v[112:115], v[66:81]
	v_exp_f32_e32 v144, v232
	v_add_f32_e32 v132, v140, v132
	v_exp_f32_e32 v145, v233
	v_add_f32_e32 v132, v141, v132
	v_exp_f32_e32 v146, v234
	v_add_f32_e32 v132, v142, v132
	v_exp_f32_e32 v147, v235
	v_add_f32_e32 v132, v143, v132
	v_exp_f32_e32 v230, v236
	v_add_f32_e32 v132, v144, v132
	v_add_f32_e32 v132, v145, v132
	v_exp_f32_e32 v232, v238
	v_add_f32_e32 v132, v146, v132
	v_exp_f32_e32 v233, v239
	v_add_f32_e32 v132, v147, v132
	v_exp_f32_e32 v234, v240
	v_add_f32_e32 v132, v230, v132
	v_exp_f32_e32 v235, v241
	v_add_f32_e32 v132, v231, v132
	v_exp_f32_e32 v236, v242
	v_add_f32_e32 v132, v232, v132
	v_add_f32_e32 v132, v233, v132
	v_add_f32_e32 v132, v234, v132
	v_add_f32_e32 v132, v235, v132
	v_add_f32_e32 v132, v236, v132
	v_add_f32_e32 v228, v237, v132
	ds_bpermute_b32 v229, v187, v228
	v_cvt_pk_bf16_f32 v132, v125, v128
	v_cvt_pk_bf16_f32 v133, v129, v133
	v_cvt_pk_bf16_f32 v134, v134, v135
	v_cvt_pk_bf16_f32 v135, v136, v137
	v_cvt_pk_bf16_f32 v136, v98, v99
	v_cvt_pk_bf16_f32 v137, v124, v126
	v_cvt_pk_bf16_f32 v138, v127, v130
	v_cvt_pk_bf16_f32 v139, v131, v139
	v_cvt_pk_bf16_f32 v140, v140, v141
	v_cvt_pk_bf16_f32 v141, v142, v143
	v_cvt_pk_bf16_f32 v142, v144, v145
	v_cvt_pk_bf16_f32 v143, v146, v147
	v_cvt_pk_bf16_f32 v144, v230, v231
	v_cvt_pk_bf16_f32 v145, v232, v233
	v_cvt_pk_bf16_f32 v146, v234, v235
	v_cvt_pk_bf16_f32 v147, v236, v237
	s_nop 0
	v_permlane32_swap_b32_e32 v132, v134
	v_permlane32_swap_b32_e32 v133, v135
	v_permlane32_swap_b32_e32 v136, v138
	v_permlane32_swap_b32_e32 v137, v139
	v_permlane32_swap_b32_e32 v140, v142
	v_permlane32_swap_b32_e32 v141, v143
	v_permlane32_swap_b32_e32 v144, v146
	v_permlane32_swap_b32_e32 v145, v147
	s_waitcnt vmcnt(2)
	s_barrier
	s_lshl_b32 s45, s39, 14
	s_add_i32 s45, s45, s44
	s_mov_b32 m0, s45
	s_add_i32 s45, s45, 0x2000
	global_load_lds_dwordx4 v[120:121], off
	s_mov_b32 m0, s45
	v_lshl_add_u64 v[120:121], v[120:121], 0, s[62:63]
	global_load_lds_dwordx4 v[122:123], off
	v_lshl_add_u64 v[122:123], v[122:123], 0, s[62:63]
	v_add_u32_e32 v98, s43, v188
	ds_read_b64_tr_b16 v[230:231], v98 offset:0
	ds_read_b64_tr_b16 v[232:233], v98 offset:0x800
	ds_read_b64_tr_b16 v[234:235], v98 offset:0x1000
	ds_read_b64_tr_b16 v[236:237], v98 offset:0x1800
	ds_read_b64_tr_b16 v[238:239], v98 offset:0x2000
	ds_read_b64_tr_b16 v[240:241], v98 offset:0x2800
	ds_read_b64_tr_b16 v[242:243], v98 offset:0x3000
	ds_read_b64_tr_b16 v[244:245], v98 offset:0x3800
	s_waitcnt lgkmcnt(0)
	s_nop 0
	v_mfma_f32_32x32x16_bf16 v[50:65], v[132:135], v[230:233], v[50:65]
	ds_read_b64_tr_b16 v[230:231], v98 offset:0x200
	ds_read_b64_tr_b16 v[232:233], v98 offset:0xa00
	v_mfma_f32_32x32x16_bf16 v[50:65], v[136:139], v[234:237], v[50:65]
	ds_read_b64_tr_b16 v[234:235], v98 offset:0x1200
	ds_read_b64_tr_b16 v[236:237], v98 offset:0x1a00
	v_mfma_f32_32x32x16_bf16 v[50:65], v[140:143], v[238:241], v[50:65]
	ds_read_b64_tr_b16 v[238:239], v98 offset:0x2200
	ds_read_b64_tr_b16 v[240:241], v98 offset:0x2a00
	v_mfma_f32_32x32x16_bf16 v[50:65], v[144:147], v[242:245], v[50:65]
	ds_read_b64_tr_b16 v[242:243], v98 offset:0x3200
	ds_read_b64_tr_b16 v[244:245], v98 offset:0x3a00
	s_waitcnt lgkmcnt(0)
	v_mfma_f32_32x32x16_bf16 v[34:49], v[132:135], v[230:233], v[34:49]
	ds_read_b64_tr_b16 v[230:231], v98 offset:0x400
	ds_read_b64_tr_b16 v[232:233], v98 offset:0xc00
	v_mfma_f32_32x32x16_bf16 v[34:49], v[136:139], v[234:237], v[34:49]
	ds_read_b64_tr_b16 v[234:235], v98 offset:0x1400
	ds_read_b64_tr_b16 v[236:237], v98 offset:0x1c00
	v_mfma_f32_32x32x16_bf16 v[34:49], v[140:143], v[238:241], v[34:49]
	ds_read_b64_tr_b16 v[238:239], v98 offset:0x2400
	ds_read_b64_tr_b16 v[240:241], v98 offset:0x2c00
	v_mfma_f32_32x32x16_bf16 v[34:49], v[144:147], v[242:245], v[34:49]
	ds_read_b64_tr_b16 v[242:243], v98 offset:0x3400
	ds_read_b64_tr_b16 v[244:245], v98 offset:0x3c00
	s_waitcnt lgkmcnt(0)
	v_mfma_f32_32x32x16_bf16 v[18:33], v[132:135], v[230:233], v[18:33]
	ds_read_b64_tr_b16 v[230:231], v98 offset:0x600
	ds_read_b64_tr_b16 v[232:233], v98 offset:0xe00
	v_mfma_f32_32x32x16_bf16 v[18:33], v[136:139], v[234:237], v[18:33]
	ds_read_b64_tr_b16 v[234:235], v98 offset:0x1600
	ds_read_b64_tr_b16 v[236:237], v98 offset:0x1e00
	v_mfma_f32_32x32x16_bf16 v[18:33], v[140:143], v[238:241], v[18:33]
	ds_read_b64_tr_b16 v[238:239], v98 offset:0x2600
	ds_read_b64_tr_b16 v[240:241], v98 offset:0x2e00
	v_mfma_f32_32x32x16_bf16 v[18:33], v[144:147], v[242:245], v[18:33]
	ds_read_b64_tr_b16 v[242:243], v98 offset:0x3600
	ds_read_b64_tr_b16 v[244:245], v98 offset:0x3e00
	s_waitcnt lgkmcnt(0)
	v_mfma_f32_32x32x16_bf16 v[2:17], v[132:135], v[230:233], v[2:17]
	v_mfma_f32_32x32x16_bf16 v[2:17], v[136:139], v[234:237], v[2:17]
	v_mfma_f32_32x32x16_bf16 v[2:17], v[140:143], v[238:241], v[2:17]
	v_mfma_f32_32x32x16_bf16 v[2:17], v[144:147], v[242:245], v[2:17]
	s_and_saveexec_b64 s[4:5], vcc
	s_cbranch_execz .LBB0_254
	flat_load_dwordx4 v[132:135], v[182:183] offset:512
	flat_load_dwordx4 v[136:139], v[182:183] offset:640
	flat_load_dwordx4 v[140:143], v[182:183] offset:544
	flat_load_dwordx4 v[144:147], v[182:183] offset:672
	flat_load_dwordx4 v[230:233], v[182:183] offset:576
	flat_load_dwordx4 v[234:237], v[182:183] offset:704
	flat_load_dwordx4 v[238:241], v[182:183] offset:608
	flat_load_dwordx4 v[242:245], v[182:183] offset:736
	s_waitcnt vmcnt(0) lgkmcnt(0)
	v_sub_u32_e32 v98, v132, v167
	v_sub_u32_e32 v132, v133, v167
	v_sub_u32_e32 v133, v137, v167
	v_sub_u32_e32 v137, v139, v167
	v_sub_u32_e32 v139, v144, v167
	v_sub_u32_e32 v144, v146, v167
	v_sub_u32_e32 v146, v230, v167
	v_sub_u32_e32 v230, v231, v167
	v_sub_u32_e32 v99, v136, v167
	v_sub_u32_e32 v134, v134, v167
	v_sub_u32_e32 v136, v138, v167
	v_sub_u32_e32 v135, v135, v167
	v_sub_u32_e32 v138, v140, v167
	v_sub_u32_e32 v140, v141, v167
	v_sub_u32_e32 v141, v145, v167
	v_sub_u32_e32 v142, v142, v167
	v_sub_u32_e32 v143, v143, v167
	v_sub_u32_e32 v145, v147, v167
	v_med3_i32 v230, v230, s87, v197
	v_med3_i32 v98, v98, s87, v197
	v_med3_i32 v99, v99, s87, v197
	v_med3_i32 v132, v132, s87, v197
	v_med3_i32 v133, v133, s87, v197
	v_med3_i32 v134, v134, s87, v197
	v_med3_i32 v136, v136, s87, v197
	v_med3_i32 v135, v135, s87, v197
	v_med3_i32 v137, v137, s87, v197
	v_med3_i32 v138, v138, s87, v197
	v_med3_i32 v139, v139, s87, v197
	v_med3_i32 v140, v140, s87, v197
	v_med3_i32 v141, v141, s87, v197
	v_med3_i32 v142, v142, s87, v197
	v_med3_i32 v144, v144, s87, v197
	v_med3_i32 v143, v143, s87, v197
	v_med3_i32 v145, v145, s87, v197
	v_lshl_add_u32 v246, v230, 2, s86
	v_sub_u32_e32 v230, v232, v167
	v_sub_u32_e32 v232, v236, v167
	v_sub_u32_e32 v147, v234, v167
	v_sub_u32_e32 v231, v235, v167
	v_lshl_add_u32 v98, v98, 2, s86
	v_lshl_add_u32 v99, v99, 2, s86
	v_lshl_add_u32 v234, v132, 2, s86
	v_lshl_add_u32 v133, v133, 2, s86
	v_lshl_add_u32 v134, v134, 2, s86
	v_lshl_add_u32 v136, v136, 2, s86
	v_lshl_add_u32 v135, v135, 2, s86
	v_lshl_add_u32 v137, v137, 2, s86
	v_lshl_add_u32 v138, v138, 2, s86
	v_lshl_add_u32 v139, v139, 2, s86
	v_lshl_add_u32 v235, v140, 2, s86
	v_lshl_add_u32 v141, v141, 2, s86
	v_lshl_add_u32 v142, v142, 2, s86
	v_lshl_add_u32 v144, v144, 2, s86
	v_lshl_add_u32 v143, v143, 2, s86
	v_lshl_add_u32 v145, v145, 2, s86
	v_med3_i32 v230, v230, s87, v197
	v_med3_i32 v232, v232, s87, v197
	ds_read_b32 v98, v98 offset:1220
	ds_read_b32 v132, v99 offset:1220
	ds_read_b32 v99, v234 offset:1220
	ds_read_b32 v133, v133 offset:1220
	ds_read_b32 v134, v134 offset:1220
	ds_read_b32 v136, v136 offset:1220
	ds_read_b32 v135, v135 offset:1220
	ds_read_b32 v137, v137 offset:1220
	ds_read_b32 v138, v138 offset:1220
	ds_read_b32 v140, v139 offset:1220
	ds_read_b32 v139, v235 offset:1220
	ds_read_b32 v141, v141 offset:1220
	ds_read_b32 v142, v142 offset:1220
	ds_read_b32 v144, v144 offset:1220
	ds_read_b32 v143, v143 offset:1220
	ds_read_b32 v145, v145 offset:1220
	v_lshl_add_u32 v234, v230, 2, s86
	v_lshl_add_u32 v235, v232, 2, s86
	v_sub_u32_e32 v230, v233, v167
	v_sub_u32_e32 v232, v237, v167
	v_med3_i32 v146, v146, s87, v197
	v_med3_i32 v147, v147, s87, v197
	v_med3_i32 v231, v231, s87, v197
	v_med3_i32 v230, v230, s87, v197
	v_med3_i32 v232, v232, s87, v197
	v_lshl_add_u32 v146, v146, 2, s86
	v_lshl_add_u32 v147, v147, 2, s86
	v_lshl_add_u32 v231, v231, 2, s86
	v_lshl_add_u32 v233, v230, 2, s86
	v_lshl_add_u32 v236, v232, 2, s86
	ds_read_b32 v146, v146 offset:1220
	ds_read_b32 v230, v147 offset:1220
	ds_read_b32 v147, v246 offset:1220
	ds_read_b32 v231, v231 offset:1220
	ds_read_b32 v232, v234 offset:1220
	ds_read_b32 v234, v235 offset:1220
	ds_read_b32 v233, v233 offset:1220
	ds_read_b32 v235, v236 offset:1220
	v_sub_u32_e32 v236, v238, v167
	v_sub_u32_e32 v238, v239, v167
	v_med3_i32 v238, v238, s87, v197
	v_sub_u32_e32 v237, v242, v167
	v_lshl_add_u32 v242, v238, 2, s86
	v_sub_u32_e32 v238, v240, v167
	v_med3_i32 v238, v238, s87, v197
	v_sub_u32_e32 v240, v244, v167
	v_sub_u32_e32 v239, v243, v167
	v_med3_i32 v240, v240, s87, v197
	v_lshl_add_u32 v243, v238, 2, s86
	v_sub_u32_e32 v238, v241, v167
	v_med3_i32 v236, v236, s87, v197
	v_med3_i32 v237, v237, s87, v197
	v_med3_i32 v239, v239, s87, v197
	v_lshl_add_u32 v244, v240, 2, s86
	v_med3_i32 v238, v238, s87, v197
	v_sub_u32_e32 v240, v245, v167
	v_lshl_add_u32 v236, v236, 2, s86
	v_lshl_add_u32 v237, v237, 2, s86
	v_lshl_add_u32 v239, v239, 2, s86
	v_med3_i32 v240, v240, s87, v197
	v_lshl_add_u32 v241, v238, 2, s86
	v_lshl_add_u32 v245, v240, 2, s86
	ds_read_b32 v236, v236 offset:1220
	ds_read_b32 v238, v237 offset:1220
	ds_read_b32 v240, v243 offset:1220
	ds_read_b32 v241, v241 offset:1220
	ds_read_b32 v237, v242 offset:1220
	ds_read_b32 v243, v245 offset:1220
	ds_read_b32 v242, v244 offset:1220
	ds_read_b32 v239, v239 offset:1220
	s_waitcnt lgkmcnt(4)
	v_pk_add_f32 v[96:97], v[96:97], v[240:241]
	s_waitcnt lgkmcnt(3)
	v_pk_add_f32 v[94:95], v[94:95], v[236:237]
	v_pk_add_f32 v[92:93], v[92:93], v[232:233]
	v_pk_add_f32 v[90:91], v[90:91], v[146:147]
	v_pk_add_f32 v[88:89], v[88:89], v[142:143]
	v_pk_add_f32 v[86:87], v[86:87], v[138:139]
	v_pk_add_f32 v[84:85], v[84:85], v[134:135]
	v_pk_add_f32 v[82:83], v[82:83], v[98:99]
	s_waitcnt lgkmcnt(1)
	v_pk_add_f32 v[80:81], v[80:81], v[242:243]
	s_waitcnt lgkmcnt(0)
	v_pk_add_f32 v[78:79], v[78:79], v[238:239]
	v_pk_add_f32 v[76:77], v[76:77], v[234:235]
	v_pk_add_f32 v[74:75], v[74:75], v[230:231]
	v_pk_add_f32 v[72:73], v[72:73], v[144:145]
	v_pk_add_f32 v[70:71], v[70:71], v[140:141]
	v_pk_add_f32 v[68:69], v[68:69], v[136:137]
	v_pk_add_f32 v[66:67], v[66:67], v[132:133]

.LBB0_262:
	s_cmpk_lt_u32 s44, 0x1000
	s_cbranch_scc0 .LskewA_out
	s_barrier
